# layer-1 kv-latent cache bf16 conversion also deferred from the prologue into idle-WG tail slots (hand-written conversion loop); layer-1 UP/DN transposes moved to layer-1 slots
# speedup vs baseline: 1.0214x; 1.0214x over previous
; DEVI u32x4 pack8(const f32x4 a, const f32x4 b) { u32x4 w; w.x = cvtpk(a[0], a[1]); w.y = cvtpk(a[2], a[3]); w.z = cvtpk(b[0], b[1]); w.w = cvtpk(b[2], b[3]); return w; }
; DEVI const float* IN(int i) { return *(const float* const __attribute__((address_space(4)))*)(kargs() + 8 * i); }
; DEVI void prologue(int wv, LAS unsigned char* lds) {
;     ...
;         const float* cache_ckv = IN(2); bf16_t* ckvb = (bf16_t*)(ws + O_CKVB);
;         for (size_t i = gt; i < (size_t)2 * MC * 256 / 8; i += 8 * NGT) {
;             f32x4 a[8], b[8];
; #pragma unroll
;             for (int k = 0; k < 8; ++k) { const size_t ii = i + k * NGT; if (ii < (size_t)2 * MC * 256 / 8) { a[k] = *(const f32x4*)(cache_ckv + ii * 8); b[k] = *(const f32x4*)(cache_ckv + ii * 8 + 4); } }
; #pragma unroll
;             for (int k = 0; k < 8; ++k) { const size_t ii = i + k * NGT; if (ii < (size_t)2 * MC * 256 / 8) *(u32x4*)(ckvb + ii * 8) = pack8(a[k], b[k]); }
;         }
.LBB0_359:
	s_mov_b64 s[24:25], 0x800000
	s_cmp_lg_u32 s52, 0x35bf
	s_cselect_b32 s24, 0x400000, s24
	s_mov_b64 s[2:3], s[0:1]
	v_cmp_gt_u64_e32 vcc, s[24:25], v[68:69]
	s_and_saveexec_b64 s[26:27], vcc
	s_cbranch_execz .LBB0_390
	s_load_dwordx2 s[28:29], s[2:3], 0x10
	s_lshl_b64 s[2:3], s[18:19], 13
	v_lshl_add_u64 v[0:1], v[64:65], 4, s[2:3]
	s_mov_b64 s[2:3], 0x3bb0800
	v_lshl_add_u64 v[66:67], v[0:1], 0, s[2:3]
	s_lshl_b64 s[2:3], s[18:19], 14
	v_lshlrev_b64 v[0:1], 5, v[64:65]
	s_lshl_b64 s[30:31], s[16:17], 16
	v_lshl_add_u64 v[70:71], s[2:3], 0, v[0:1]
	s_lshl_b64 s[34:35], s[16:17], 17
	s_lshl_b64 s[2:3], s[16:17], 10
	s_add_u32 s2, s2, s6
	s_addc_u32 s3, s3, s7
	v_lshl_add_u64 v[0:1], s[2:3], 0, v[64:65]
	s_add_u32 s2, s6, s22
	s_addc_u32 s3, s7, s23
	v_lshl_add_u64 v[76:77], s[2:3], 0, v[64:65]
	s_lshl_b64 s[36:37], s[16:17], 12
	s_mul_i32 s2, s16, 0x600
	s_mul_hi_i32 s3, s16, 0x600
	s_add_u32 s2, s2, s6
	v_mov_b64_e32 v[2:3], 0x3bb0800
	s_addc_u32 s3, s3, s7
	v_lshlrev_b64 v[72:73], 5, v[0:1]
	v_lshl_add_u64 v[74:75], v[0:1], 4, v[2:3]
	v_lshl_add_u64 v[0:1], s[2:3], 0, v[64:65]
	s_lshl_b64 s[2:3], s[16:17], 11
	s_add_u32 s2, s2, s6
	s_addc_u32 s3, s3, s7
	v_lshlrev_b64 v[78:79], 5, v[0:1]
	v_lshl_add_u64 v[80:81], v[0:1], 4, v[2:3]
	v_lshl_add_u64 v[0:1], s[2:3], 0, v[64:65]
	s_mul_i32 s2, s16, 0xa00
	s_mul_hi_i32 s3, s16, 0xa00
	s_add_u32 s2, s2, s6
	s_addc_u32 s3, s3, s7
	v_lshlrev_b64 v[84:85], 5, v[0:1]
	v_lshl_add_u64 v[86:87], v[0:1], 4, v[2:3]
	v_lshl_add_u64 v[0:1], s[2:3], 0, v[64:65]
	s_mul_i32 s2, s16, 0xe00
	s_mul_hi_i32 s3, s16, 0xe00
	s_add_u32 s2, s2, s6
	s_addc_u32 s3, s3, s7
	v_lshlrev_b64 v[90:91], 5, v[0:1]
	v_lshl_add_u64 v[92:93], v[0:1], 4, v[2:3]
	v_lshl_add_u64 v[0:1], s[2:3], 0, v[64:65]
	s_mul_i32 s2, s16, 0xc00
	s_mul_hi_i32 s3, s16, 0xc00
	s_add_u32 s2, s2, s6
	s_addc_u32 s3, s3, s7
	v_lshl_add_u64 v[4:5], s[2:3], 0, v[64:65]
	v_lshlrev_b64 v[96:97], 5, v[4:5]
	v_lshlrev_b64 v[100:101], 5, v[0:1]
	v_or_b32_e32 v72, 16, v72
	v_or_b32_e32 v78, 16, v78
	v_lshlrev_b64 v[82:83], 5, v[76:77]
	v_or_b32_e32 v84, 16, v84
	v_lshl_add_u64 v[88:89], v[76:77], 4, v[2:3]
	v_or_b32_e32 v90, 16, v90
	v_lshl_add_u64 v[94:95], v[0:1], 4, v[2:3]
	v_or_b32_e32 v96, 16, v96
	v_lshl_add_u64 v[98:99], v[4:5], 4, v[2:3]
	v_or_b32_e32 v100, 16, v100
	v_bfe_u32 v0, v70, 5, 10
	v_and_b32_e32 v70, 0xffff801f, v70
	v_and_b32_e32 v2, 31, v0
	v_lshl_or_b32 v70, v2, 10, v70
	v_lshrrev_b32_e32 v2, 8, v0
	v_lshl_or_b32 v70, v2, 8, v70
	v_bfe_u32 v2, v0, 5, 1
	v_lshl_or_b32 v70, v2, 7, v70
	v_bfe_u32 v2, v0, 6, 2
	v_lshl_or_b32 v70, v2, 5, v70
	v_bfe_u32 v0, v82, 5, 10
	v_and_b32_e32 v82, 0xffff801f, v82
	v_and_b32_e32 v2, 31, v0
	v_lshl_or_b32 v82, v2, 10, v82
	v_lshrrev_b32_e32 v2, 8, v0
	v_lshl_or_b32 v82, v2, 8, v82
	v_bfe_u32 v2, v0, 5, 1
	v_lshl_or_b32 v82, v2, 7, v82
	v_bfe_u32 v2, v0, 6, 2
	v_lshl_or_b32 v82, v2, 5, v82
	v_bfe_u32 v0, v72, 5, 10
	v_and_b32_e32 v72, 0xffff801f, v72
	v_and_b32_e32 v2, 31, v0
	v_lshl_or_b32 v72, v2, 10, v72
	v_lshrrev_b32_e32 v2, 8, v0
	v_lshl_or_b32 v72, v2, 8, v72
	v_bfe_u32 v2, v0, 5, 1
	v_lshl_or_b32 v72, v2, 7, v72
	v_bfe_u32 v2, v0, 6, 2
	v_lshl_or_b32 v72, v2, 5, v72
	v_bfe_u32 v0, v78, 5, 10
	v_and_b32_e32 v78, 0xffff801f, v78
	v_and_b32_e32 v2, 31, v0
	v_lshl_or_b32 v78, v2, 10, v78
	v_lshrrev_b32_e32 v2, 8, v0
	v_lshl_or_b32 v78, v2, 8, v78
	v_bfe_u32 v2, v0, 5, 1
	v_lshl_or_b32 v78, v2, 7, v78
	v_bfe_u32 v2, v0, 6, 2
	v_lshl_or_b32 v78, v2, 5, v78
	v_bfe_u32 v0, v84, 5, 10
	v_and_b32_e32 v84, 0xffff801f, v84
	v_and_b32_e32 v2, 31, v0
	v_lshl_or_b32 v84, v2, 10, v84
	v_lshrrev_b32_e32 v2, 8, v0
	v_lshl_or_b32 v84, v2, 8, v84
	v_bfe_u32 v2, v0, 5, 1
	v_lshl_or_b32 v84, v2, 7, v84
	v_bfe_u32 v2, v0, 6, 2
	v_lshl_or_b32 v84, v2, 5, v84
	v_bfe_u32 v0, v90, 5, 10
	v_and_b32_e32 v90, 0xffff801f, v90
	v_and_b32_e32 v2, 31, v0
	v_lshl_or_b32 v90, v2, 10, v90
	v_lshrrev_b32_e32 v2, 8, v0
	v_lshl_or_b32 v90, v2, 8, v90
	v_bfe_u32 v2, v0, 5, 1
	v_lshl_or_b32 v90, v2, 7, v90
	v_bfe_u32 v2, v0, 6, 2
	v_lshl_or_b32 v90, v2, 5, v90
	v_bfe_u32 v0, v96, 5, 10
	v_and_b32_e32 v96, 0xffff801f, v96
	v_and_b32_e32 v2, 31, v0
	v_lshl_or_b32 v96, v2, 10, v96
	v_lshrrev_b32_e32 v2, 8, v0
	v_lshl_or_b32 v96, v2, 8, v96
	v_bfe_u32 v2, v0, 5, 1
	v_lshl_or_b32 v96, v2, 7, v96
	v_bfe_u32 v2, v0, 6, 2
	v_lshl_or_b32 v96, v2, 5, v96
	v_bfe_u32 v0, v100, 5, 10
	v_and_b32_e32 v100, 0xffff801f, v100
	v_and_b32_e32 v2, 31, v0
	v_lshl_or_b32 v100, v2, 10, v100
	v_lshrrev_b32_e32 v2, 8, v0
	v_lshl_or_b32 v100, v2, 8, v100
	v_bfe_u32 v2, v0, 5, 1
	v_lshl_or_b32 v100, v2, 7, v100
	v_bfe_u32 v2, v0, 6, 2
	v_lshl_or_b32 v100, v2, 5, v100
	s_mov_b64 s[38:39], 0
	s_mov_b64 s[40:41], 0x7fffff
	s_cmp_lg_u32 s52, 0x35bf
	s_cselect_b32 s40, 0x3fffff, s40
	s_waitcnt lgkmcnt(0)
	s_mov_b64 s[42:43], s[20:21]
	s_branch .LBB0_362

; DEVI u32x4 pack8(const f32x4 a, const f32x4 b) { u32x4 w; w.x = cvtpk(a[0], a[1]); w.y = cvtpk(a[2], a[3]); w.z = cvtpk(b[0], b[1]); w.w = cvtpk(b[2], b[3]); return w; }
; DEVI const float* IN(int i) { return *(const float* const __attribute__((address_space(4)))*)(kargs() + 8 * i); }
; #define WL(l, o) ((const bf16_t*)(WSP() + O_W + (size_t)(l) * W_LAYER + (o)))
; #define WSB(o) ((const bf16_t*)(WSP() + (o)))
; DEVI void prologue(int wv, LAS unsigned char* lds) {
;     ...
;         const float* cache_ckv = IN(2); bf16_t* ckvb = (bf16_t*)(ws + O_CKVB);
;         for (size_t i = gt; i < (size_t)2 * MC * 256 / 8; i += 8 * NGT) {
;             f32x4 a[8], b[8];
; #pragma unroll
;             for (int k = 0; k < 8; ++k) { const size_t ii = i + k * NGT; if (ii < (size_t)2 * MC * 256 / 8) { a[k] = *(const f32x4*)(cache_ckv + ii * 8); b[k] = *(const f32x4*)(cache_ckv + ii * 8 + 4); } }
; #pragma unroll
;             for (int k = 0; k < 8; ++k) { const size_t ii = i + k * NGT; if (ii < (size_t)2 * MC * 256 / 8) *(u32x4*)(ckvb + ii * 8) = pack8(a[k], b[k]); }
;         }
; __global__ void __launch_bounds__(512, 2) fwd_kernel(Args args_unused) {
;     ...
;         { EpiZ E{l}; run_gemm(wv, lds, WSB(O_XB), WL(l, W_IN), 1024, 1024, MT, NZ, 1024, off, E); }
;         grid_bar(wv, lds);
.LBB0_715:
	s_waitcnt vmcnt(0) lgkmcnt(0)
	s_load_dword vcc_lo, s[0:1], 0xb8
	v_readlane_b32 vcc_hi, v255, 5
	s_waitcnt lgkmcnt(0)
	s_cmp_lg_u32 vcc_lo, 0x100
	s_cbranch_scc1 .Lsj_skip1
	s_sub_i32 vcc_hi, vcc_hi, 154
	s_and_b32 vcc_hi, vcc_hi, 0xff
	s_cmp_ge_u32 vcc_hi, 102
	s_cbranch_scc1 .Lsj_skip1
	v_readlane_b32 vcc_lo, v255, 0
	v_writelane_b32 v201, s0, 0
	v_writelane_b32 v201, s1, 1
	v_writelane_b32 v201, s2, 2
	v_writelane_b32 v201, s3, 3
	v_writelane_b32 v201, s4, 4
	v_writelane_b32 v201, s5, 5
	v_writelane_b32 v201, s6, 6
	v_writelane_b32 v201, s7, 7
	v_writelane_b32 v201, s8, 8
	v_writelane_b32 v201, s9, 9
	v_writelane_b32 v201, s10, 10
	v_writelane_b32 v201, s11, 11
	v_writelane_b32 v201, s12, 12
	v_writelane_b32 v201, s13, 13
	v_writelane_b32 v201, s14, 14
	v_writelane_b32 v201, s15, 15
	v_writelane_b32 v201, s16, 16
	v_writelane_b32 v201, s17, 17
	v_writelane_b32 v201, s18, 18
	v_writelane_b32 v201, s19, 19
	v_writelane_b32 v201, s20, 20
	v_writelane_b32 v201, s21, 21
	v_writelane_b32 v201, s22, 22
	v_writelane_b32 v201, s23, 23
	v_writelane_b32 v201, s24, 24
	v_writelane_b32 v201, s25, 25
	v_writelane_b32 v201, s26, 26
	v_writelane_b32 v201, s27, 27
	v_writelane_b32 v201, s28, 28
	v_writelane_b32 v201, s29, 29
	v_writelane_b32 v201, s30, 30
	v_writelane_b32 v201, s31, 31
	v_writelane_b32 v201, s32, 32
	v_writelane_b32 v201, s33, 33
	v_writelane_b32 v201, s34, 34
	v_writelane_b32 v201, s35, 35
	v_writelane_b32 v201, s36, 36
	v_writelane_b32 v201, s37, 37
	v_writelane_b32 v201, s38, 38
	v_writelane_b32 v201, s39, 39
	v_writelane_b32 v201, s40, 40
	v_writelane_b32 v201, s41, 41
	v_writelane_b32 v201, s42, 42
	v_writelane_b32 v201, s43, 43
	v_writelane_b32 v201, s44, 44
	v_writelane_b32 v201, s45, 45
	v_writelane_b32 v201, s46, 46
	v_writelane_b32 v201, s47, 47
	v_writelane_b32 v201, s48, 48
	v_writelane_b32 v201, s49, 49
	v_writelane_b32 v201, s50, 50
	v_writelane_b32 v201, s51, 51
	v_writelane_b32 v201, s52, 52
	v_writelane_b32 v201, s53, 53
	v_writelane_b32 v201, s54, 54
	v_writelane_b32 v201, s55, 55
	v_writelane_b32 v201, s56, 56
	v_writelane_b32 v201, s57, 57
	v_writelane_b32 v201, s58, 58
	v_writelane_b32 v201, s59, 59
	v_writelane_b32 v201, s60, 60
	v_writelane_b32 v201, s61, 61
	v_writelane_b32 v201, s62, 62
	v_writelane_b32 v201, s63, 63
	v_writelane_b32 v202, s64, 0
	v_writelane_b32 v202, s65, 1
	v_writelane_b32 v202, s66, 2
	v_writelane_b32 v202, s67, 3
	v_writelane_b32 v202, s68, 4
	v_writelane_b32 v202, s69, 5
	v_writelane_b32 v202, s70, 6
	v_writelane_b32 v202, s71, 7
	v_writelane_b32 v202, s72, 8
	v_writelane_b32 v202, s73, 9
	v_writelane_b32 v202, s74, 10
	v_writelane_b32 v202, s75, 11
	v_writelane_b32 v202, s76, 12
	v_writelane_b32 v202, s77, 13
	v_writelane_b32 v202, s78, 14
	v_writelane_b32 v202, s79, 15
	v_writelane_b32 v202, s80, 16
	v_writelane_b32 v202, s81, 17
	v_writelane_b32 v202, s82, 18
	v_writelane_b32 v202, s83, 19
	v_writelane_b32 v202, s84, 20
	v_writelane_b32 v202, s85, 21
	v_writelane_b32 v202, s86, 22
	v_writelane_b32 v202, s87, 23
	v_writelane_b32 v202, s88, 24
	v_writelane_b32 v202, s89, 25
	v_writelane_b32 v202, s90, 26
	v_writelane_b32 v202, s91, 27
	v_writelane_b32 v202, s92, 28
	v_writelane_b32 v202, s93, 29
	v_writelane_b32 v202, s94, 30
	v_writelane_b32 v202, s95, 31
	v_writelane_b32 v202, s96, 32
	v_writelane_b32 v202, s97, 33
	v_writelane_b32 v202, s98, 34
	v_writelane_b32 v202, s99, 35
	v_mov_b32_e32 v200, v1
	s_mov_b32 s54, 0
	s_mov_b32 s52, -1
	s_cmp_lg_u32 vcc_lo, 0
	s_cbranch_scc0 .Lsj_par1
	s_mov_b32 s54, 2784
	s_mov_b32 s52, 3599
.Lsj_par1:
	s_cmp_gt_i32 s54, s52
	s_cbranch_scc1 .Lsj_ret1
	s_mov_b32 s16, 102
	s_mov_b32 s18, vcc_hi
	s_mov_b32 s53, 1
	s_mov_b64 s[6:7], s[0:1]
	s_branch .Lsj_entry
.Lsj_ret1:
	v_readlane_b32 vcc_lo, v255, 0
	s_cmp_lg_u32 vcc_lo, 0
	s_cbranch_scc1 .Lsjd_no1_1
	v_readlane_b32 s2, v201, 0
	v_readlane_b32 s3, v201, 1
	v_readlane_b32 s4, v201, 33
	v_readlane_b32 s5, v255, 5
	s_nop 7
	s_load_dwordx2 s[6:7], s[2:3], 0x10
	s_load_dwordx2 s[8:9], s[2:3], 0xb0
	s_sub_i32 s5, s5, 154
	s_and_b32 s5, s5, 0xff
	s_lshl_b32 s5, s5, 9
	v_mbcnt_lo_u32_b32 v0, -1, 0
	v_mbcnt_hi_u32_b32 v0, -1, v0
	v_lshl_or_b32 v0, s4, 6, v0
	v_add_u32_e32 v0, s5, v0
	v_add_u32_e32 v0, 0x780000, v0
	s_mov_b32 s10, 0x800000
	s_waitcnt lgkmcnt(0)
	s_add_u32 s8, s8, 0x3bb0800
	s_addc_u32 s9, s9, 0
; DEVI u32x4 pack8(const f32x4 a, const f32x4 b) { u32x4 w; w.x = cvtpk(a[0], a[1]); w.y = cvtpk(a[2], a[3]); w.z = cvtpk(b[0], b[1]); w.w = cvtpk(b[2], b[3]); return w; }
; DEVI const float* IN(int i) { return *(const float* const __attribute__((address_space(4)))*)(kargs() + 8 * i); }
; DEVI void prologue(int wv, LAS unsigned char* lds) {
;     ...
;         const float* cache_ckv = IN(2); bf16_t* ckvb = (bf16_t*)(ws + O_CKVB);
;         for (size_t i = gt; i < (size_t)2 * MC * 256 / 8; i += 8 * NGT) {
;             f32x4 a[8], b[8];
; #pragma unroll
;             for (int k = 0; k < 8; ++k) { const size_t ii = i + k * NGT; if (ii < (size_t)2 * MC * 256 / 8) { a[k] = *(const f32x4*)(cache_ckv + ii * 8); b[k] = *(const f32x4*)(cache_ckv + ii * 8 + 4); } }
; #pragma unroll
;             for (int k = 0; k < 8; ++k) { const size_t ii = i + k * NGT; if (ii < (size_t)2 * MC * 256 / 8) *(u32x4*)(ckvb + ii * 8) = pack8(a[k], b[k]); }
;         }
.Lsjd_loop1_1:
	v_mov_b32_e32 v1, v0
	v_cmp_gt_u32_e64 s[12:13], s10, v1
	v_add_u32_e32 v2, 0xcc00, v0
	v_cmp_gt_u32_e64 s[14:15], s10, v2
	v_add_u32_e32 v3, 0x19800, v0
	v_cmp_gt_u32_e64 s[16:17], s10, v3
	v_add_u32_e32 v4, 0x26400, v0
	v_cmp_gt_u32_e64 s[18:19], s10, v4
	v_add_u32_e32 v5, 0x33000, v0
	v_cmp_gt_u32_e64 s[20:21], s10, v5
	v_add_u32_e32 v6, 0x3fc00, v0
	v_cmp_gt_u32_e64 s[22:23], s10, v6
	v_add_u32_e32 v7, 0x4c800, v0
	v_cmp_gt_u32_e64 s[24:25], s10, v7
	v_add_u32_e32 v8, 0x59400, v0
	v_cmp_gt_u32_e64 s[26:27], s10, v8
	s_mov_b64 exec, s[12:13]
	v_and_b32_e32 v20, 0x3ff, v1
	v_and_b32_e32 v21, 0xfffffc00, v1
	v_lshlrev_b32_e32 v21, 5, v21
	v_and_b32_e32 v22, 31, v20
	v_lshl_or_b32 v21, v22, 10, v21
	v_lshrrev_b32_e32 v22, 8, v20
	v_lshl_or_b32 v21, v22, 8, v21
	v_bfe_u32 v22, v20, 5, 1
	v_lshl_or_b32 v21, v22, 7, v21
	v_bfe_u32 v22, v20, 6, 2
	v_lshl_or_b32 v9, v22, 5, v21
	global_load_dwordx4 v[24:27], v9, s[6:7]
	global_load_dwordx4 v[28:31], v9, s[6:7] offset:16
	s_mov_b64 exec, s[14:15]
	v_and_b32_e32 v20, 0x3ff, v2
	v_and_b32_e32 v21, 0xfffffc00, v2
	v_lshlrev_b32_e32 v21, 5, v21
	v_and_b32_e32 v22, 31, v20
	v_lshl_or_b32 v21, v22, 10, v21
	v_lshrrev_b32_e32 v22, 8, v20
	v_lshl_or_b32 v21, v22, 8, v21
	v_bfe_u32 v22, v20, 5, 1
	v_lshl_or_b32 v21, v22, 7, v21
	v_bfe_u32 v22, v20, 6, 2
	v_lshl_or_b32 v10, v22, 5, v21
	global_load_dwordx4 v[32:35], v10, s[6:7]
	global_load_dwordx4 v[36:39], v10, s[6:7] offset:16
	s_mov_b64 exec, s[16:17]
	v_and_b32_e32 v20, 0x3ff, v3
	v_and_b32_e32 v21, 0xfffffc00, v3
	v_lshlrev_b32_e32 v21, 5, v21
	v_and_b32_e32 v22, 31, v20
	v_lshl_or_b32 v21, v22, 10, v21
	v_lshrrev_b32_e32 v22, 8, v20
	v_lshl_or_b32 v21, v22, 8, v21
	v_bfe_u32 v22, v20, 5, 1
	v_lshl_or_b32 v21, v22, 7, v21
	v_bfe_u32 v22, v20, 6, 2
	v_lshl_or_b32 v11, v22, 5, v21
	global_load_dwordx4 v[40:43], v11, s[6:7]
	global_load_dwordx4 v[44:47], v11, s[6:7] offset:16
	s_mov_b64 exec, s[18:19]
	v_and_b32_e32 v20, 0x3ff, v4
	v_and_b32_e32 v21, 0xfffffc00, v4
	v_lshlrev_b32_e32 v21, 5, v21
	v_and_b32_e32 v22, 31, v20
	v_lshl_or_b32 v21, v22, 10, v21
	v_lshrrev_b32_e32 v22, 8, v20
	v_lshl_or_b32 v21, v22, 8, v21
	v_bfe_u32 v22, v20, 5, 1
	v_lshl_or_b32 v21, v22, 7, v21
	v_bfe_u32 v22, v20, 6, 2
	v_lshl_or_b32 v12, v22, 5, v21
	global_load_dwordx4 v[48:51], v12, s[6:7]
	global_load_dwordx4 v[52:55], v12, s[6:7] offset:16
	s_mov_b64 exec, s[20:21]
	v_and_b32_e32 v20, 0x3ff, v5
	v_and_b32_e32 v21, 0xfffffc00, v5
	v_lshlrev_b32_e32 v21, 5, v21
	v_and_b32_e32 v22, 31, v20
	v_lshl_or_b32 v21, v22, 10, v21
	v_lshrrev_b32_e32 v22, 8, v20
	v_lshl_or_b32 v21, v22, 8, v21
	v_bfe_u32 v22, v20, 5, 1
	v_lshl_or_b32 v21, v22, 7, v21
	v_bfe_u32 v22, v20, 6, 2
	v_lshl_or_b32 v13, v22, 5, v21
	global_load_dwordx4 v[56:59], v13, s[6:7]
	global_load_dwordx4 v[60:63], v13, s[6:7] offset:16
	s_mov_b64 exec, s[22:23]
	v_and_b32_e32 v20, 0x3ff, v6
	v_and_b32_e32 v21, 0xfffffc00, v6
	v_lshlrev_b32_e32 v21, 5, v21
	v_and_b32_e32 v22, 31, v20
	v_lshl_or_b32 v21, v22, 10, v21
	v_lshrrev_b32_e32 v22, 8, v20
	v_lshl_or_b32 v21, v22, 8, v21
	v_bfe_u32 v22, v20, 5, 1
	v_lshl_or_b32 v21, v22, 7, v21
	v_bfe_u32 v22, v20, 6, 2
	v_lshl_or_b32 v14, v22, 5, v21
	global_load_dwordx4 v[64:67], v14, s[6:7]
	global_load_dwordx4 v[68:71], v14, s[6:7] offset:16
	s_mov_b64 exec, s[24:25]
	v_and_b32_e32 v20, 0x3ff, v7
	v_and_b32_e32 v21, 0xfffffc00, v7
	v_lshlrev_b32_e32 v21, 5, v21
	v_and_b32_e32 v22, 31, v20
	v_lshl_or_b32 v21, v22, 10, v21
	v_lshrrev_b32_e32 v22, 8, v20
	v_lshl_or_b32 v21, v22, 8, v21
	v_bfe_u32 v22, v20, 5, 1
	v_lshl_or_b32 v21, v22, 7, v21
	v_bfe_u32 v22, v20, 6, 2
	v_lshl_or_b32 v15, v22, 5, v21
	global_load_dwordx4 v[72:75], v15, s[6:7]
	global_load_dwordx4 v[76:79], v15, s[6:7] offset:16
	s_mov_b64 exec, s[26:27]
	v_and_b32_e32 v20, 0x3ff, v8
	v_and_b32_e32 v21, 0xfffffc00, v8
	v_lshlrev_b32_e32 v21, 5, v21
	v_and_b32_e32 v22, 31, v20
	v_lshl_or_b32 v21, v22, 10, v21
	v_lshrrev_b32_e32 v22, 8, v20
	v_lshl_or_b32 v21, v22, 8, v21
	v_bfe_u32 v22, v20, 5, 1
	v_lshl_or_b32 v21, v22, 7, v21
	v_bfe_u32 v22, v20, 6, 2
	v_lshl_or_b32 v16, v22, 5, v21
	global_load_dwordx4 v[80:83], v16, s[6:7]
	global_load_dwordx4 v[84:87], v16, s[6:7] offset:16
	s_mov_b64 exec, s[12:13]
	s_waitcnt vmcnt(14)
	v_cvt_pk_bf16_f32 v100, v24, v25
	v_cvt_pk_bf16_f32 v101, v26, v27
	v_cvt_pk_bf16_f32 v102, v28, v29
	v_cvt_pk_bf16_f32 v103, v30, v31
	v_lshlrev_b32_e32 v104, 4, v1
	global_store_dwordx4 v104, v[100:103], s[8:9]
	s_mov_b64 exec, s[14:15]
	s_waitcnt vmcnt(12)
	v_cvt_pk_bf16_f32 v106, v32, v33
	v_cvt_pk_bf16_f32 v107, v34, v35
	v_cvt_pk_bf16_f32 v108, v36, v37
	v_cvt_pk_bf16_f32 v109, v38, v39
	v_lshlrev_b32_e32 v110, 4, v2
	global_store_dwordx4 v110, v[106:109], s[8:9]
	s_mov_b64 exec, s[16:17]
	s_waitcnt vmcnt(10)
	v_cvt_pk_bf16_f32 v100, v40, v41
	v_cvt_pk_bf16_f32 v101, v42, v43
	v_cvt_pk_bf16_f32 v102, v44, v45
	v_cvt_pk_bf16_f32 v103, v46, v47
	v_lshlrev_b32_e32 v104, 4, v3
	global_store_dwordx4 v104, v[100:103], s[8:9]
	s_mov_b64 exec, s[18:19]
	s_waitcnt vmcnt(8)
	v_cvt_pk_bf16_f32 v106, v48, v49
	v_cvt_pk_bf16_f32 v107, v50, v51
	v_cvt_pk_bf16_f32 v108, v52, v53
	v_cvt_pk_bf16_f32 v109, v54, v55
	v_lshlrev_b32_e32 v110, 4, v4
	global_store_dwordx4 v110, v[106:109], s[8:9]
	s_mov_b64 exec, s[20:21]
	s_waitcnt vmcnt(6)
	v_cvt_pk_bf16_f32 v100, v56, v57
	v_cvt_pk_bf16_f32 v101, v58, v59
	v_cvt_pk_bf16_f32 v102, v60, v61
	v_cvt_pk_bf16_f32 v103, v62, v63
	v_lshlrev_b32_e32 v104, 4, v5
	global_store_dwordx4 v104, v[100:103], s[8:9]
	s_mov_b64 exec, s[22:23]
	s_waitcnt vmcnt(4)
	v_cvt_pk_bf16_f32 v106, v64, v65
	v_cvt_pk_bf16_f32 v107, v66, v67
	v_cvt_pk_bf16_f32 v108, v68, v69
	v_cvt_pk_bf16_f32 v109, v70, v71
	v_lshlrev_b32_e32 v110, 4, v6
	global_store_dwordx4 v110, v[106:109], s[8:9]
	s_mov_b64 exec, s[24:25]
	s_waitcnt vmcnt(2)
	v_cvt_pk_bf16_f32 v100, v72, v73
	v_cvt_pk_bf16_f32 v101, v74, v75
	v_cvt_pk_bf16_f32 v102, v76, v77
	v_cvt_pk_bf16_f32 v103, v78, v79
	v_lshlrev_b32_e32 v104, 4, v7
	global_store_dwordx4 v104, v[100:103], s[8:9]
	s_mov_b64 exec, s[26:27]
	s_waitcnt vmcnt(0)
	v_cvt_pk_bf16_f32 v106, v80, v81
	v_cvt_pk_bf16_f32 v107, v82, v83
	v_cvt_pk_bf16_f32 v108, v84, v85
	v_cvt_pk_bf16_f32 v109, v86, v87
	v_lshlrev_b32_e32 v110, 4, v8
	global_store_dwordx4 v110, v[106:109], s[8:9]
	s_mov_b64 exec, -1
	v_add_u32_e32 v0, 0x66000, v0
	v_cmp_gt_u32_e32 vcc, s10, v0
	s_and_b64 vcc, exec, vcc
	s_cbranch_scc1 .Lsjd_loop1_1

; DEVI const float* IN(int i) { return *(const float* const __attribute__((address_space(4)))*)(kargs() + 8 * i); }
; DEVI void prologue(int wv, LAS unsigned char* lds) {
;     ...
;     for (int it = gw; it < 2 * I_L; it += NGW) {
;         const int l = it / I_L; int r = it % I_L;
;         unsigned char* wl = ws + O_W + (size_t)l * W_LAYER;
;         if (r < I_IN) { const int kb = r / 101, nb = r % 101, n0 = nb * 32;
;             const int d0 = n0 < 384 ? n0 : n0 < 640 ? 512 + (n0 - 384) : n0 < 672 ? 384 + (n0 - 640) : n0 < 1184 ? 768 + (n0 - 672) : n0 < 2208 ? 1280 + (n0 - 1184) : 2304 + (n0 - 2208);
;             tr_item(IN(6) + (size_t)l * 1024 * 3232, 3232, 1024, IN(5) + l * 1024, (bf16_t*)(wl + W_IN), d0, scr, kb * 64, n0, lane); continue; }
;         r -= I_IN;
;         if (r < I_UQ) { const int kb = r / 24, nb = r % 24, n0 = nb * 32, hd = n0 / 96, dim0 = n0 % 96;
;             const int d0 = dim0 < 64 ? 256 * (hd >> 2) + 128 * (dim0 >> 5) + 32 * (hd & 3) : 512 + 128 * (hd >> 2) + 32 * (hd & 3);
;             tr_item(IN(9) + (size_t)l * 384 * 768, 768, 384, IN(7) + l * 384, (bf16_t*)(wl + W_UQ), d0, scr, kb * 64, n0, lane); continue; }
;         r -= I_UQ;
;         if (r < 2 * I_KV) { const int fold = r < I_KV; if (!fold) r -= I_KV;
;             const int kb = r / 32, nb = r % 32, n0 = nb * 32, hd = n0 / 128, dim0 = n0 % 128;
;             const bool isk = dim0 < 64;
;             const int d0 = isk ? 256 * (hd >> 2) + 128 * (dim0 >> 5) + 32 * (hd & 3) : hd * 64 + (dim0 - 64);
;             bf16_t* dst = (bf16_t*)(wl + (fold ? (isk ? W_K : W_V) : (isk ? W_KC : W_VC)));
;             tr_item(IN(10) + (size_t)l * 256 * 1024, 1024, 256, fold ? IN(8) + l * 256 : nullptr, dst, d0, scr, kb * 64, n0, lane); continue; }
;         r -= 2 * I_KV;
;         if (r < I_A) { tr_item(IN(13) + (size_t)l * 512 * 1024, 1024, 512, nullptr, (bf16_t*)(wl + W_A), (r % 32) * 32, scr, (r / 32) * 64, (r % 32) * 32, lane); continue; }
;         r -= I_A;
;         if (r < I_O) { tr_item(IN(17) + (size_t)l * 1024 * 1024, 1024, 1024, nullptr, (bf16_t*)(wl + W_O), (r % 32) * 32, scr, (r / 32) * 64, (r % 32) * 32, lane); continue; }
;         r -= I_O;
;         if (r < I_UP) { tr_item(IN(19) + (size_t)l * 1024 * 4096, 4096, 1024, IN(18) + l * 1024, (bf16_t*)(wl + W_UP), (r % 128) * 32, scr, (r / 128) * 64, (r % 128) * 32, lane); continue; }
;         r -= I_UP;
.LBB0_1230:
	s_waitcnt vmcnt(0) lgkmcnt(0)
	s_load_dword vcc_lo, s[0:1], 0xb8
	v_readlane_b32 vcc_hi, v255, 5
	s_waitcnt lgkmcnt(0)
	s_cmp_lg_u32 vcc_lo, 0x100
	s_cbranch_scc1 .Lsj_skip2
	s_sub_i32 vcc_hi, vcc_hi, 32
	s_and_b32 vcc_hi, vcc_hi, 0xff
	s_cmp_ge_u32 vcc_hi, 122
	s_cbranch_scc1 .Lsj_skip2
	v_readlane_b32 vcc_lo, v255, 0
	v_writelane_b32 v201, s0, 0
	v_writelane_b32 v201, s1, 1
	v_writelane_b32 v201, s2, 2
	v_writelane_b32 v201, s3, 3
	v_writelane_b32 v201, s4, 4
	v_writelane_b32 v201, s5, 5
	v_writelane_b32 v201, s6, 6
	v_writelane_b32 v201, s7, 7
	v_writelane_b32 v201, s8, 8
	v_writelane_b32 v201, s9, 9
	v_writelane_b32 v201, s10, 10
	v_writelane_b32 v201, s11, 11
	v_writelane_b32 v201, s12, 12
	v_writelane_b32 v201, s13, 13
	v_writelane_b32 v201, s14, 14
	v_writelane_b32 v201, s15, 15
	v_writelane_b32 v201, s16, 16
	v_writelane_b32 v201, s17, 17
	v_writelane_b32 v201, s18, 18
	v_writelane_b32 v201, s19, 19
	v_writelane_b32 v201, s20, 20
	v_writelane_b32 v201, s21, 21
	v_writelane_b32 v201, s22, 22
	v_writelane_b32 v201, s23, 23
	v_writelane_b32 v201, s24, 24
	v_writelane_b32 v201, s25, 25
	v_writelane_b32 v201, s26, 26
	v_writelane_b32 v201, s27, 27
	v_writelane_b32 v201, s28, 28
	v_writelane_b32 v201, s29, 29
	v_writelane_b32 v201, s30, 30
	v_writelane_b32 v201, s31, 31
	v_writelane_b32 v201, s32, 32
	v_writelane_b32 v201, s33, 33
	v_writelane_b32 v201, s34, 34
	v_writelane_b32 v201, s35, 35
	v_writelane_b32 v201, s36, 36
	v_writelane_b32 v201, s37, 37
	v_writelane_b32 v201, s38, 38
	v_writelane_b32 v201, s39, 39
	v_writelane_b32 v201, s40, 40
	v_writelane_b32 v201, s41, 41
	v_writelane_b32 v201, s42, 42
	v_writelane_b32 v201, s43, 43
	v_writelane_b32 v201, s44, 44
	v_writelane_b32 v201, s45, 45
	v_writelane_b32 v201, s46, 46
	v_writelane_b32 v201, s47, 47
	v_writelane_b32 v201, s48, 48
	v_writelane_b32 v201, s49, 49
	v_writelane_b32 v201, s50, 50
	v_writelane_b32 v201, s51, 51
	v_writelane_b32 v201, s52, 52
	v_writelane_b32 v201, s53, 53
	v_writelane_b32 v201, s54, 54
	v_writelane_b32 v201, s55, 55
	v_writelane_b32 v201, s56, 56
	v_writelane_b32 v201, s57, 57
	v_writelane_b32 v201, s58, 58
	v_writelane_b32 v201, s59, 59
	v_writelane_b32 v201, s60, 60
	v_writelane_b32 v201, s61, 61
	v_writelane_b32 v201, s62, 62
	v_writelane_b32 v201, s63, 63
	v_writelane_b32 v202, s64, 0
	v_writelane_b32 v202, s65, 1
	v_writelane_b32 v202, s66, 2
	v_writelane_b32 v202, s67, 3
	v_writelane_b32 v202, s68, 4
	v_writelane_b32 v202, s69, 5
	v_writelane_b32 v202, s70, 6
	v_writelane_b32 v202, s71, 7
	v_writelane_b32 v202, s72, 8
	v_writelane_b32 v202, s73, 9
	v_writelane_b32 v202, s74, 10
	v_writelane_b32 v202, s75, 11
	v_writelane_b32 v202, s76, 12
	v_writelane_b32 v202, s77, 13
	v_writelane_b32 v202, s78, 14
	v_writelane_b32 v202, s79, 15
	v_writelane_b32 v202, s80, 16
	v_writelane_b32 v202, s81, 17
	v_writelane_b32 v202, s82, 18
	v_writelane_b32 v202, s83, 19
	v_writelane_b32 v202, s84, 20
	v_writelane_b32 v202, s85, 21
	v_writelane_b32 v202, s86, 22
	v_writelane_b32 v202, s87, 23
	v_writelane_b32 v202, s88, 24
	v_writelane_b32 v202, s89, 25
	v_writelane_b32 v202, s90, 26
	v_writelane_b32 v202, s91, 27
	v_writelane_b32 v202, s92, 28
	v_writelane_b32 v202, s93, 29
	v_writelane_b32 v202, s94, 30
	v_writelane_b32 v202, s95, 31
	v_writelane_b32 v202, s96, 32
	v_writelane_b32 v202, s97, 33
	v_writelane_b32 v202, s98, 34
	v_writelane_b32 v202, s99, 35
	v_mov_b32_e32 v200, v1
	s_mov_b32 s54, 9664
	s_mov_b32 s52, 10639
	s_cmp_lg_u32 vcc_lo, 0
	s_cbranch_scc0 .Lsj_par2
	s_mov_b32 s54, 3600
	s_mov_b32 s52, 4575
.Lsj_par2:
	s_cmp_gt_i32 s54, s52
	s_cbranch_scc1 .Lsj_ret2
	s_mov_b32 s16, 122
	s_mov_b32 s18, vcc_hi
	s_mov_b32 s53, 2
	s_mov_b64 s[6:7], s[0:1]

; DEVI void prologue(int wv, LAS unsigned char* lds) {
;     ...
;     for (int it = gw; it < 2 * I_L; it += NGW) {
;         const int l = it / I_L; int r = it % I_L;
.Lsj_end:
	s_mov_b64 exec, -1
	s_waitcnt lgkmcnt(0)
	s_cmp_eq_u32 s53, 1
	s_cbranch_scc1 .Lsj_ret1
	s_cmp_eq_u32 s53, 4
	s_cbranch_scc1 .Lsj_ret4
	s_cmp_eq_u32 s53, 5
	s_cbranch_scc1 .Lsj_ret5

; DEVI const float* IN(int i) { return *(const float* const __attribute__((address_space(4)))*)(kargs() + 8 * i); }
; DEVI void prologue(int wv, LAS unsigned char* lds) {
;     ...
;     for (int it = gw; it < 2 * I_L; it += NGW) {
;         const int l = it / I_L; int r = it % I_L;
;         unsigned char* wl = ws + O_W + (size_t)l * W_LAYER;
;         if (r < I_IN) { const int kb = r / 101, nb = r % 101, n0 = nb * 32;
;             const int d0 = n0 < 384 ? n0 : n0 < 640 ? 512 + (n0 - 384) : n0 < 672 ? 384 + (n0 - 640) : n0 < 1184 ? 768 + (n0 - 672) : n0 < 2208 ? 1280 + (n0 - 1184) : 2304 + (n0 - 2208);
;             tr_item(IN(6) + (size_t)l * 1024 * 3232, 3232, 1024, IN(5) + l * 1024, (bf16_t*)(wl + W_IN), d0, scr, kb * 64, n0, lane); continue; }
;         r -= I_IN;
;         if (r < I_UQ) { const int kb = r / 24, nb = r % 24, n0 = nb * 32, hd = n0 / 96, dim0 = n0 % 96;
;             const int d0 = dim0 < 64 ? 256 * (hd >> 2) + 128 * (dim0 >> 5) + 32 * (hd & 3) : 512 + 128 * (hd >> 2) + 32 * (hd & 3);
;             tr_item(IN(9) + (size_t)l * 384 * 768, 768, 384, IN(7) + l * 384, (bf16_t*)(wl + W_UQ), d0, scr, kb * 64, n0, lane); continue; }
;         r -= I_UQ;
;         if (r < 2 * I_KV) { const int fold = r < I_KV; if (!fold) r -= I_KV;
;             const int kb = r / 32, nb = r % 32, n0 = nb * 32, hd = n0 / 128, dim0 = n0 % 128;
;             const bool isk = dim0 < 64;
;             const int d0 = isk ? 256 * (hd >> 2) + 128 * (dim0 >> 5) + 32 * (hd & 3) : hd * 64 + (dim0 - 64);
;             bf16_t* dst = (bf16_t*)(wl + (fold ? (isk ? W_K : W_V) : (isk ? W_KC : W_VC)));
;             tr_item(IN(10) + (size_t)l * 256 * 1024, 1024, 256, fold ? IN(8) + l * 256 : nullptr, dst, d0, scr, kb * 64, n0, lane); continue; }
;         r -= 2 * I_KV;
;         if (r < I_A) { tr_item(IN(13) + (size_t)l * 512 * 1024, 1024, 512, nullptr, (bf16_t*)(wl + W_A), (r % 32) * 32, scr, (r / 32) * 64, (r % 32) * 32, lane); continue; }
;         r -= I_A;
;         if (r < I_O) { tr_item(IN(17) + (size_t)l * 1024 * 1024, 1024, 1024, nullptr, (bf16_t*)(wl + W_O), (r % 32) * 32, scr, (r / 32) * 64, (r % 32) * 32, lane); continue; }
;         r -= I_O;
;         if (r < I_UP) { tr_item(IN(19) + (size_t)l * 1024 * 4096, 4096, 1024, IN(18) + l * 1024, (bf16_t*)(wl + W_UP), (r % 128) * 32, scr, (r / 128) * 64, (r % 128) * 32, lane); continue; }
;         r -= I_UP;
.LBB0_1468:
	s_waitcnt vmcnt(0) lgkmcnt(0)
	s_load_dword vcc_lo, s[0:1], 0xb8
	v_readlane_b32 vcc_hi, v255, 5
	s_waitcnt lgkmcnt(0)
	s_cmp_lg_u32 vcc_lo, 0x100
	s_cbranch_scc1 .Lsj_skip4
	s_sub_i32 vcc_hi, vcc_hi, 48
	s_and_b32 vcc_hi, vcc_hi, 0xff
	s_cmp_ge_u32 vcc_hi, 248
	s_cbranch_scc1 .Lsj_skip4
	v_readlane_b32 vcc_lo, v255, 0
	v_writelane_b32 v201, s0, 0
	v_writelane_b32 v201, s1, 1
	v_writelane_b32 v201, s2, 2
	v_writelane_b32 v201, s3, 3
	v_writelane_b32 v201, s4, 4
	v_writelane_b32 v201, s5, 5
	v_writelane_b32 v201, s6, 6
	v_writelane_b32 v201, s7, 7
	v_writelane_b32 v201, s8, 8
	v_writelane_b32 v201, s9, 9
	v_writelane_b32 v201, s10, 10
	v_writelane_b32 v201, s11, 11
	v_writelane_b32 v201, s12, 12
	v_writelane_b32 v201, s13, 13
	v_writelane_b32 v201, s14, 14
	v_writelane_b32 v201, s15, 15
	v_writelane_b32 v201, s16, 16
	v_writelane_b32 v201, s17, 17
	v_writelane_b32 v201, s18, 18
	v_writelane_b32 v201, s19, 19
	v_writelane_b32 v201, s20, 20
	v_writelane_b32 v201, s21, 21
	v_writelane_b32 v201, s22, 22
	v_writelane_b32 v201, s23, 23
	v_writelane_b32 v201, s24, 24
	v_writelane_b32 v201, s25, 25
	v_writelane_b32 v201, s26, 26
	v_writelane_b32 v201, s27, 27
	v_writelane_b32 v201, s28, 28
	v_writelane_b32 v201, s29, 29
	v_writelane_b32 v201, s30, 30
	v_writelane_b32 v201, s31, 31
	v_writelane_b32 v201, s32, 32
	v_writelane_b32 v201, s33, 33
	v_writelane_b32 v201, s34, 34
	v_writelane_b32 v201, s35, 35
	v_writelane_b32 v201, s36, 36
	v_writelane_b32 v201, s37, 37
	v_writelane_b32 v201, s38, 38
	v_writelane_b32 v201, s39, 39
	v_writelane_b32 v201, s40, 40
	v_writelane_b32 v201, s41, 41
	v_writelane_b32 v201, s42, 42
	v_writelane_b32 v201, s43, 43
	v_writelane_b32 v201, s44, 44
	v_writelane_b32 v201, s45, 45
	v_writelane_b32 v201, s46, 46
	v_writelane_b32 v201, s47, 47
	v_writelane_b32 v201, s48, 48
	v_writelane_b32 v201, s49, 49
	v_writelane_b32 v201, s50, 50
	v_writelane_b32 v201, s51, 51
	v_writelane_b32 v201, s52, 52
	v_writelane_b32 v201, s53, 53
	v_writelane_b32 v201, s54, 54
	v_writelane_b32 v201, s55, 55
	v_writelane_b32 v201, s56, 56
	v_writelane_b32 v201, s57, 57
	v_writelane_b32 v201, s58, 58
	v_writelane_b32 v201, s59, 59
	v_writelane_b32 v201, s60, 60
	v_writelane_b32 v201, s61, 61
	v_writelane_b32 v201, s62, 62
	v_writelane_b32 v201, s63, 63
	v_writelane_b32 v202, s64, 0
	v_writelane_b32 v202, s65, 1
	v_writelane_b32 v202, s66, 2
	v_writelane_b32 v202, s67, 3
	v_writelane_b32 v202, s68, 4
	v_writelane_b32 v202, s69, 5
	v_writelane_b32 v202, s70, 6
	v_writelane_b32 v202, s71, 7
	v_writelane_b32 v202, s72, 8
	v_writelane_b32 v202, s73, 9
	v_writelane_b32 v202, s74, 10
	v_writelane_b32 v202, s75, 11
	v_writelane_b32 v202, s76, 12
	v_writelane_b32 v202, s77, 13
	v_writelane_b32 v202, s78, 14
	v_writelane_b32 v202, s79, 15
	v_writelane_b32 v202, s80, 16
	v_writelane_b32 v202, s81, 17
	v_writelane_b32 v202, s82, 18
	v_writelane_b32 v202, s83, 19
	v_writelane_b32 v202, s84, 20
	v_writelane_b32 v202, s85, 21
	v_writelane_b32 v202, s86, 22
	v_writelane_b32 v202, s87, 23
	v_writelane_b32 v202, s88, 24
	v_writelane_b32 v202, s89, 25
	v_writelane_b32 v202, s90, 26
	v_writelane_b32 v202, s91, 27
	v_writelane_b32 v202, s92, 28
	v_writelane_b32 v202, s93, 29
	v_writelane_b32 v202, s94, 30
	v_writelane_b32 v202, s95, 31
	v_writelane_b32 v202, s96, 32
	v_writelane_b32 v202, s97, 33
	v_writelane_b32 v202, s98, 34
	v_writelane_b32 v202, s99, 35
	v_mov_b32_e32 v200, v1
	s_mov_b32 s54, 10640
	s_mov_b32 s52, 12623
	s_cmp_lg_u32 vcc_lo, 0
	s_cbranch_scc0 .Lsj_par4
	s_mov_b32 s54, 4576
	s_mov_b32 s52, 6559
.Lsj_par4:
	s_cmp_gt_i32 s54, s52
	s_cbranch_scc1 .Lsj_ret4
	s_mov_b32 s16, 248
	s_mov_b32 s18, vcc_hi
	s_mov_b32 s53, 4
	s_mov_b64 s[6:7], s[0:1]
	s_branch .Lsj_entry
.Lsj_ret4:
	v_readlane_b32 vcc_lo, v255, 0
	s_cmp_eq_u32 vcc_lo, 0
	s_cbranch_scc1 .Lsjd_no4_0
	v_readlane_b32 s2, v201, 0
	v_readlane_b32 s3, v201, 1
	v_readlane_b32 s4, v201, 33
	v_readlane_b32 s5, v255, 5
	s_nop 7
	s_load_dwordx2 s[6:7], s[2:3], 0x10
	s_load_dwordx2 s[8:9], s[2:3], 0xb0
	s_sub_i32 s5, s5, 48
	s_and_b32 s5, s5, 0xff
	s_lshl_b32 s5, s5, 9
	v_mbcnt_lo_u32_b32 v0, -1, 0
	v_mbcnt_hi_u32_b32 v0, -1, v0
	v_lshl_or_b32 v0, s4, 6, v0
	v_add_u32_e32 v0, s5, v0
	v_add_u32_e32 v0, 0x400000, v0
	s_mov_b32 s10, 0x4c0000
	s_waitcnt lgkmcnt(0)
	s_add_u32 s8, s8, 0x3bb0800
	s_addc_u32 s9, s9, 0
; DEVI u32x4 pack8(const f32x4 a, const f32x4 b) { u32x4 w; w.x = cvtpk(a[0], a[1]); w.y = cvtpk(a[2], a[3]); w.z = cvtpk(b[0], b[1]); w.w = cvtpk(b[2], b[3]); return w; }
; DEVI const float* IN(int i) { return *(const float* const __attribute__((address_space(4)))*)(kargs() + 8 * i); }
; DEVI void prologue(int wv, LAS unsigned char* lds) {
;     ...
;         const float* cache_ckv = IN(2); bf16_t* ckvb = (bf16_t*)(ws + O_CKVB);
;         for (size_t i = gt; i < (size_t)2 * MC * 256 / 8; i += 8 * NGT) {
;             f32x4 a[8], b[8];
; #pragma unroll
;             for (int k = 0; k < 8; ++k) { const size_t ii = i + k * NGT; if (ii < (size_t)2 * MC * 256 / 8) { a[k] = *(const f32x4*)(cache_ckv + ii * 8); b[k] = *(const f32x4*)(cache_ckv + ii * 8 + 4); } }
; #pragma unroll
;             for (int k = 0; k < 8; ++k) { const size_t ii = i + k * NGT; if (ii < (size_t)2 * MC * 256 / 8) *(u32x4*)(ckvb + ii * 8) = pack8(a[k], b[k]); }
;         }
.Lsjd_loop4_0:
	v_mov_b32_e32 v1, v0
	v_cmp_gt_u32_e64 s[12:13], s10, v1
	v_add_u32_e32 v2, 0x1f000, v0
	v_cmp_gt_u32_e64 s[14:15], s10, v2
	v_add_u32_e32 v3, 0x3e000, v0
	v_cmp_gt_u32_e64 s[16:17], s10, v3
	v_add_u32_e32 v4, 0x5d000, v0
	v_cmp_gt_u32_e64 s[18:19], s10, v4
	v_add_u32_e32 v5, 0x7c000, v0
	v_cmp_gt_u32_e64 s[20:21], s10, v5
	v_add_u32_e32 v6, 0x9b000, v0
	v_cmp_gt_u32_e64 s[22:23], s10, v6
	v_add_u32_e32 v7, 0xba000, v0
	v_cmp_gt_u32_e64 s[24:25], s10, v7
	v_add_u32_e32 v8, 0xd9000, v0
	v_cmp_gt_u32_e64 s[26:27], s10, v8
	s_mov_b64 exec, s[12:13]
	v_and_b32_e32 v20, 0x3ff, v1
	v_and_b32_e32 v21, 0xfffffc00, v1
	v_lshlrev_b32_e32 v21, 5, v21
	v_and_b32_e32 v22, 31, v20
	v_lshl_or_b32 v21, v22, 10, v21
	v_lshrrev_b32_e32 v22, 8, v20
	v_lshl_or_b32 v21, v22, 8, v21
	v_bfe_u32 v22, v20, 5, 1
	v_lshl_or_b32 v21, v22, 7, v21
	v_bfe_u32 v22, v20, 6, 2
	v_lshl_or_b32 v9, v22, 5, v21
	global_load_dwordx4 v[24:27], v9, s[6:7]
	global_load_dwordx4 v[28:31], v9, s[6:7] offset:16
	s_mov_b64 exec, s[14:15]
	v_and_b32_e32 v20, 0x3ff, v2
	v_and_b32_e32 v21, 0xfffffc00, v2
	v_lshlrev_b32_e32 v21, 5, v21
	v_and_b32_e32 v22, 31, v20
	v_lshl_or_b32 v21, v22, 10, v21
	v_lshrrev_b32_e32 v22, 8, v20
	v_lshl_or_b32 v21, v22, 8, v21
	v_bfe_u32 v22, v20, 5, 1
	v_lshl_or_b32 v21, v22, 7, v21
	v_bfe_u32 v22, v20, 6, 2
	v_lshl_or_b32 v10, v22, 5, v21
	global_load_dwordx4 v[32:35], v10, s[6:7]
	global_load_dwordx4 v[36:39], v10, s[6:7] offset:16
	s_mov_b64 exec, s[16:17]
	v_and_b32_e32 v20, 0x3ff, v3
	v_and_b32_e32 v21, 0xfffffc00, v3
	v_lshlrev_b32_e32 v21, 5, v21
	v_and_b32_e32 v22, 31, v20
	v_lshl_or_b32 v21, v22, 10, v21
	v_lshrrev_b32_e32 v22, 8, v20
	v_lshl_or_b32 v21, v22, 8, v21
	v_bfe_u32 v22, v20, 5, 1
	v_lshl_or_b32 v21, v22, 7, v21
	v_bfe_u32 v22, v20, 6, 2
	v_lshl_or_b32 v11, v22, 5, v21
	global_load_dwordx4 v[40:43], v11, s[6:7]
	global_load_dwordx4 v[44:47], v11, s[6:7] offset:16
	s_mov_b64 exec, s[18:19]
	v_and_b32_e32 v20, 0x3ff, v4
	v_and_b32_e32 v21, 0xfffffc00, v4
	v_lshlrev_b32_e32 v21, 5, v21
	v_and_b32_e32 v22, 31, v20
	v_lshl_or_b32 v21, v22, 10, v21
	v_lshrrev_b32_e32 v22, 8, v20
	v_lshl_or_b32 v21, v22, 8, v21
	v_bfe_u32 v22, v20, 5, 1
	v_lshl_or_b32 v21, v22, 7, v21
	v_bfe_u32 v22, v20, 6, 2
	v_lshl_or_b32 v12, v22, 5, v21
	global_load_dwordx4 v[48:51], v12, s[6:7]
	global_load_dwordx4 v[52:55], v12, s[6:7] offset:16
	s_mov_b64 exec, s[20:21]
	v_and_b32_e32 v20, 0x3ff, v5
	v_and_b32_e32 v21, 0xfffffc00, v5
	v_lshlrev_b32_e32 v21, 5, v21
	v_and_b32_e32 v22, 31, v20
	v_lshl_or_b32 v21, v22, 10, v21
	v_lshrrev_b32_e32 v22, 8, v20
	v_lshl_or_b32 v21, v22, 8, v21
	v_bfe_u32 v22, v20, 5, 1
	v_lshl_or_b32 v21, v22, 7, v21
	v_bfe_u32 v22, v20, 6, 2
	v_lshl_or_b32 v13, v22, 5, v21
	global_load_dwordx4 v[56:59], v13, s[6:7]
	global_load_dwordx4 v[60:63], v13, s[6:7] offset:16
	s_mov_b64 exec, s[22:23]
	v_and_b32_e32 v20, 0x3ff, v6
	v_and_b32_e32 v21, 0xfffffc00, v6
	v_lshlrev_b32_e32 v21, 5, v21
	v_and_b32_e32 v22, 31, v20
	v_lshl_or_b32 v21, v22, 10, v21
	v_lshrrev_b32_e32 v22, 8, v20
	v_lshl_or_b32 v21, v22, 8, v21
	v_bfe_u32 v22, v20, 5, 1
	v_lshl_or_b32 v21, v22, 7, v21
	v_bfe_u32 v22, v20, 6, 2
	v_lshl_or_b32 v14, v22, 5, v21
	global_load_dwordx4 v[64:67], v14, s[6:7]
	global_load_dwordx4 v[68:71], v14, s[6:7] offset:16
	s_mov_b64 exec, s[24:25]
	v_and_b32_e32 v20, 0x3ff, v7
	v_and_b32_e32 v21, 0xfffffc00, v7
	v_lshlrev_b32_e32 v21, 5, v21
	v_and_b32_e32 v22, 31, v20
	v_lshl_or_b32 v21, v22, 10, v21
	v_lshrrev_b32_e32 v22, 8, v20
	v_lshl_or_b32 v21, v22, 8, v21
	v_bfe_u32 v22, v20, 5, 1
	v_lshl_or_b32 v21, v22, 7, v21
	v_bfe_u32 v22, v20, 6, 2
	v_lshl_or_b32 v15, v22, 5, v21
	global_load_dwordx4 v[72:75], v15, s[6:7]
	global_load_dwordx4 v[76:79], v15, s[6:7] offset:16
	s_mov_b64 exec, s[26:27]
	v_and_b32_e32 v20, 0x3ff, v8
	v_and_b32_e32 v21, 0xfffffc00, v8
	v_lshlrev_b32_e32 v21, 5, v21
	v_and_b32_e32 v22, 31, v20
	v_lshl_or_b32 v21, v22, 10, v21
	v_lshrrev_b32_e32 v22, 8, v20
	v_lshl_or_b32 v21, v22, 8, v21
	v_bfe_u32 v22, v20, 5, 1
	v_lshl_or_b32 v21, v22, 7, v21
	v_bfe_u32 v22, v20, 6, 2
	v_lshl_or_b32 v16, v22, 5, v21
	global_load_dwordx4 v[80:83], v16, s[6:7]
	global_load_dwordx4 v[84:87], v16, s[6:7] offset:16
	s_mov_b64 exec, s[12:13]
	s_waitcnt vmcnt(14)
	v_cvt_pk_bf16_f32 v100, v24, v25
	v_cvt_pk_bf16_f32 v101, v26, v27
	v_cvt_pk_bf16_f32 v102, v28, v29
	v_cvt_pk_bf16_f32 v103, v30, v31
	v_lshlrev_b32_e32 v104, 4, v1
	global_store_dwordx4 v104, v[100:103], s[8:9]
	s_mov_b64 exec, s[14:15]
	s_waitcnt vmcnt(12)
	v_cvt_pk_bf16_f32 v106, v32, v33
	v_cvt_pk_bf16_f32 v107, v34, v35
	v_cvt_pk_bf16_f32 v108, v36, v37
	v_cvt_pk_bf16_f32 v109, v38, v39
	v_lshlrev_b32_e32 v110, 4, v2
	global_store_dwordx4 v110, v[106:109], s[8:9]
	s_mov_b64 exec, s[16:17]
	s_waitcnt vmcnt(10)
	v_cvt_pk_bf16_f32 v100, v40, v41
	v_cvt_pk_bf16_f32 v101, v42, v43
	v_cvt_pk_bf16_f32 v102, v44, v45
	v_cvt_pk_bf16_f32 v103, v46, v47
	v_lshlrev_b32_e32 v104, 4, v3
	global_store_dwordx4 v104, v[100:103], s[8:9]
	s_mov_b64 exec, s[18:19]
	s_waitcnt vmcnt(8)
	v_cvt_pk_bf16_f32 v106, v48, v49
	v_cvt_pk_bf16_f32 v107, v50, v51
	v_cvt_pk_bf16_f32 v108, v52, v53
	v_cvt_pk_bf16_f32 v109, v54, v55
	v_lshlrev_b32_e32 v110, 4, v4
	global_store_dwordx4 v110, v[106:109], s[8:9]
	s_mov_b64 exec, s[20:21]
	s_waitcnt vmcnt(6)
	v_cvt_pk_bf16_f32 v100, v56, v57
	v_cvt_pk_bf16_f32 v101, v58, v59
	v_cvt_pk_bf16_f32 v102, v60, v61
	v_cvt_pk_bf16_f32 v103, v62, v63
	v_lshlrev_b32_e32 v104, 4, v5
	global_store_dwordx4 v104, v[100:103], s[8:9]
	s_mov_b64 exec, s[22:23]
	s_waitcnt vmcnt(4)
	v_cvt_pk_bf16_f32 v106, v64, v65
	v_cvt_pk_bf16_f32 v107, v66, v67
	v_cvt_pk_bf16_f32 v108, v68, v69
	v_cvt_pk_bf16_f32 v109, v70, v71
	v_lshlrev_b32_e32 v110, 4, v6
	global_store_dwordx4 v110, v[106:109], s[8:9]
	s_mov_b64 exec, s[24:25]
	s_waitcnt vmcnt(2)
	v_cvt_pk_bf16_f32 v100, v72, v73
	v_cvt_pk_bf16_f32 v101, v74, v75
	v_cvt_pk_bf16_f32 v102, v76, v77
	v_cvt_pk_bf16_f32 v103, v78, v79
	v_lshlrev_b32_e32 v104, 4, v7
	global_store_dwordx4 v104, v[100:103], s[8:9]
	s_mov_b64 exec, s[26:27]
	s_waitcnt vmcnt(0)
	v_cvt_pk_bf16_f32 v106, v80, v81
	v_cvt_pk_bf16_f32 v107, v82, v83
	v_cvt_pk_bf16_f32 v108, v84, v85
	v_cvt_pk_bf16_f32 v109, v86, v87
	v_lshlrev_b32_e32 v110, 4, v8
	global_store_dwordx4 v110, v[106:109], s[8:9]
	s_mov_b64 exec, -1
	v_add_u32_e32 v0, 0xf8000, v0
	v_cmp_gt_u32_e32 vcc, s10, v0
	s_and_b64 vcc, exec, vcc
	s_cbranch_scc1 .Lsjd_loop4_0

; DEVI const float* IN(int i) { return *(const float* const __attribute__((address_space(4)))*)(kargs() + 8 * i); }
; DEVI void prologue(int wv, LAS unsigned char* lds) {
;     ...
;     for (int it = gw; it < 2 * I_L; it += NGW) {
;         const int l = it / I_L; int r = it % I_L;
;         unsigned char* wl = ws + O_W + (size_t)l * W_LAYER;
;         if (r < I_IN) { const int kb = r / 101, nb = r % 101, n0 = nb * 32;
;             const int d0 = n0 < 384 ? n0 : n0 < 640 ? 512 + (n0 - 384) : n0 < 672 ? 384 + (n0 - 640) : n0 < 1184 ? 768 + (n0 - 672) : n0 < 2208 ? 1280 + (n0 - 1184) : 2304 + (n0 - 2208);
;             tr_item(IN(6) + (size_t)l * 1024 * 3232, 3232, 1024, IN(5) + l * 1024, (bf16_t*)(wl + W_IN), d0, scr, kb * 64, n0, lane); continue; }
;         r -= I_IN;
;         if (r < I_UQ) { const int kb = r / 24, nb = r % 24, n0 = nb * 32, hd = n0 / 96, dim0 = n0 % 96;
;             const int d0 = dim0 < 64 ? 256 * (hd >> 2) + 128 * (dim0 >> 5) + 32 * (hd & 3) : 512 + 128 * (hd >> 2) + 32 * (hd & 3);
;             tr_item(IN(9) + (size_t)l * 384 * 768, 768, 384, IN(7) + l * 384, (bf16_t*)(wl + W_UQ), d0, scr, kb * 64, n0, lane); continue; }
;         r -= I_UQ;
;         if (r < 2 * I_KV) { const int fold = r < I_KV; if (!fold) r -= I_KV;
;             const int kb = r / 32, nb = r % 32, n0 = nb * 32, hd = n0 / 128, dim0 = n0 % 128;
;             const bool isk = dim0 < 64;
;             const int d0 = isk ? 256 * (hd >> 2) + 128 * (dim0 >> 5) + 32 * (hd & 3) : hd * 64 + (dim0 - 64);
;             bf16_t* dst = (bf16_t*)(wl + (fold ? (isk ? W_K : W_V) : (isk ? W_KC : W_VC)));
;             tr_item(IN(10) + (size_t)l * 256 * 1024, 1024, 256, fold ? IN(8) + l * 256 : nullptr, dst, d0, scr, kb * 64, n0, lane); continue; }
;         r -= 2 * I_KV;
;         if (r < I_A) { tr_item(IN(13) + (size_t)l * 512 * 1024, 1024, 512, nullptr, (bf16_t*)(wl + W_A), (r % 32) * 32, scr, (r / 32) * 64, (r % 32) * 32, lane); continue; }
;         r -= I_A;
;         if (r < I_O) { tr_item(IN(17) + (size_t)l * 1024 * 1024, 1024, 1024, nullptr, (bf16_t*)(wl + W_O), (r % 32) * 32, scr, (r / 32) * 64, (r % 32) * 32, lane); continue; }
;         r -= I_O;
;         if (r < I_UP) { tr_item(IN(19) + (size_t)l * 1024 * 4096, 4096, 1024, IN(18) + l * 1024, (bf16_t*)(wl + W_UP), (r % 128) * 32, scr, (r / 128) * 64, (r % 128) * 32, lane); continue; }
;         r -= I_UP;
.LBB0_1559:
	s_waitcnt vmcnt(0) lgkmcnt(0)
	s_load_dword vcc_lo, s[0:1], 0xb8
	v_readlane_b32 vcc_hi, v255, 5
	s_waitcnt lgkmcnt(0)
	s_cmp_lg_u32 vcc_lo, 0x100
	s_cbranch_scc1 .Lsj_skip5
	s_sub_i32 vcc_hi, vcc_hi, 56
	s_and_b32 vcc_hi, vcc_hi, 0xff
	s_cmp_ge_u32 vcc_hi, 248
	s_cbranch_scc1 .Lsj_skip5
	v_readlane_b32 vcc_lo, v255, 0
	v_writelane_b32 v201, s0, 0
	v_writelane_b32 v201, s1, 1
	v_writelane_b32 v201, s2, 2
	v_writelane_b32 v201, s3, 3
	v_writelane_b32 v201, s4, 4
	v_writelane_b32 v201, s5, 5
	v_writelane_b32 v201, s6, 6
	v_writelane_b32 v201, s7, 7
	v_writelane_b32 v201, s8, 8
	v_writelane_b32 v201, s9, 9
	v_writelane_b32 v201, s10, 10
	v_writelane_b32 v201, s11, 11
	v_writelane_b32 v201, s12, 12
	v_writelane_b32 v201, s13, 13
	v_writelane_b32 v201, s14, 14
	v_writelane_b32 v201, s15, 15
	v_writelane_b32 v201, s16, 16
	v_writelane_b32 v201, s17, 17
	v_writelane_b32 v201, s18, 18
	v_writelane_b32 v201, s19, 19
	v_writelane_b32 v201, s20, 20
	v_writelane_b32 v201, s21, 21
	v_writelane_b32 v201, s22, 22
	v_writelane_b32 v201, s23, 23
	v_writelane_b32 v201, s24, 24
	v_writelane_b32 v201, s25, 25
	v_writelane_b32 v201, s26, 26
	v_writelane_b32 v201, s27, 27
	v_writelane_b32 v201, s28, 28
	v_writelane_b32 v201, s29, 29
	v_writelane_b32 v201, s30, 30
	v_writelane_b32 v201, s31, 31
	v_writelane_b32 v201, s32, 32
	v_writelane_b32 v201, s33, 33
	v_writelane_b32 v201, s34, 34
	v_writelane_b32 v201, s35, 35
	v_writelane_b32 v201, s36, 36
	v_writelane_b32 v201, s37, 37
	v_writelane_b32 v201, s38, 38
	v_writelane_b32 v201, s39, 39
	v_writelane_b32 v201, s40, 40
	v_writelane_b32 v201, s41, 41
	v_writelane_b32 v201, s42, 42
	v_writelane_b32 v201, s43, 43
	v_writelane_b32 v201, s44, 44
	v_writelane_b32 v201, s45, 45
	v_writelane_b32 v201, s46, 46
	v_writelane_b32 v201, s47, 47
	v_writelane_b32 v201, s48, 48
	v_writelane_b32 v201, s49, 49
	v_writelane_b32 v201, s50, 50
	v_writelane_b32 v201, s51, 51
	v_writelane_b32 v201, s52, 52
	v_writelane_b32 v201, s53, 53
	v_writelane_b32 v201, s54, 54
	v_writelane_b32 v201, s55, 55
	v_writelane_b32 v201, s56, 56
	v_writelane_b32 v201, s57, 57
	v_writelane_b32 v201, s58, 58
	v_writelane_b32 v201, s59, 59
	v_writelane_b32 v201, s60, 60
	v_writelane_b32 v201, s61, 61
	v_writelane_b32 v201, s62, 62
	v_writelane_b32 v201, s63, 63
	v_writelane_b32 v202, s64, 0
	v_writelane_b32 v202, s65, 1
	v_writelane_b32 v202, s66, 2
	v_writelane_b32 v202, s67, 3
	v_writelane_b32 v202, s68, 4
	v_writelane_b32 v202, s69, 5
	v_writelane_b32 v202, s70, 6
	v_writelane_b32 v202, s71, 7
	v_writelane_b32 v202, s72, 8
	v_writelane_b32 v202, s73, 9
	v_writelane_b32 v202, s74, 10
	v_writelane_b32 v202, s75, 11
	v_writelane_b32 v202, s76, 12
	v_writelane_b32 v202, s77, 13
	v_writelane_b32 v202, s78, 14
	v_writelane_b32 v202, s79, 15
	v_writelane_b32 v202, s80, 16
	v_writelane_b32 v202, s81, 17
	v_writelane_b32 v202, s82, 18
	v_writelane_b32 v202, s83, 19
	v_writelane_b32 v202, s84, 20
	v_writelane_b32 v202, s85, 21
	v_writelane_b32 v202, s86, 22
	v_writelane_b32 v202, s87, 23
	v_writelane_b32 v202, s88, 24
	v_writelane_b32 v202, s89, 25
	v_writelane_b32 v202, s90, 26
	v_writelane_b32 v202, s91, 27
	v_writelane_b32 v202, s92, 28
	v_writelane_b32 v202, s93, 29
	v_writelane_b32 v202, s94, 30
	v_writelane_b32 v202, s95, 31
	v_writelane_b32 v202, s96, 32
	v_writelane_b32 v202, s97, 33
	v_writelane_b32 v202, s98, 34
	v_writelane_b32 v202, s99, 35
	v_mov_b32_e32 v200, v1
	s_mov_b32 s54, 12624
	s_mov_b32 s52, 13759
	s_cmp_lg_u32 vcc_lo, 0
	s_cbranch_scc0 .Lsj_par5
	s_mov_b32 s54, 6560
	s_mov_b32 s52, 9663
.Lsj_par5:
	s_cmp_gt_i32 s54, s52
	s_cbranch_scc1 .Lsj_ret5
	s_mov_b32 s16, 248
	s_mov_b32 s18, vcc_hi
	s_mov_b32 s53, 5
	s_mov_b64 s[6:7], s[0:1]
	s_branch .Lsj_entry
.Lsj_ret5:
	v_readlane_b32 vcc_lo, v255, 0
	s_cmp_eq_u32 vcc_lo, 0
	s_cbranch_scc1 .Lsjd_no5_0
	v_readlane_b32 s2, v201, 0
	v_readlane_b32 s3, v201, 1
	v_readlane_b32 s4, v201, 33
	v_readlane_b32 s5, v255, 5
	s_nop 7
	s_load_dwordx2 s[6:7], s[2:3], 0x10
	s_load_dwordx2 s[8:9], s[2:3], 0xb0
	s_sub_i32 s5, s5, 56
	s_and_b32 s5, s5, 0xff
	s_lshl_b32 s5, s5, 9
	v_mbcnt_lo_u32_b32 v0, -1, 0
	v_mbcnt_hi_u32_b32 v0, -1, v0
	v_lshl_or_b32 v0, s4, 6, v0
	v_add_u32_e32 v0, s5, v0
	v_add_u32_e32 v0, 0x4c0000, v0
	s_mov_b32 s10, 0x5c0000
	s_waitcnt lgkmcnt(0)
	s_add_u32 s8, s8, 0x3bb0800
	s_addc_u32 s9, s9, 0

; DEVI const float* IN(int i) { return *(const float* const __attribute__((address_space(4)))*)(kargs() + 8 * i); }
; DEVI void prologue(int wv, LAS unsigned char* lds) {
;     ...
;         const float* cache_ckv = IN(2); bf16_t* ckvb = (bf16_t*)(ws + O_CKVB);
;         for (size_t i = gt; i < (size_t)2 * MC * 256 / 8; i += 8 * NGT) {
;             f32x4 a[8], b[8];
; #pragma unroll
;             for (int k = 0; k < 8; ++k) { const size_t ii = i + k * NGT; if (ii < (size_t)2 * MC * 256 / 8) { a[k] = *(const f32x4*)(cache_ckv + ii * 8); b[k] = *(const f32x4*)(cache_ckv + ii * 8 + 4); } }
.LBB0_1627:
	s_waitcnt vmcnt(0) lgkmcnt(0)
	s_load_dword vcc_lo, s[0:1], 0xb8
	v_readlane_b32 vcc_hi, v255, 5
	s_waitcnt lgkmcnt(0)
	s_cmp_lg_u32 vcc_lo, 0x100
	s_cbranch_scc1 .Lsj_skip6
	s_sub_i32 vcc_hi, vcc_hi, 88
	s_and_b32 vcc_hi, vcc_hi, 0xff
	s_cmp_ge_u32 vcc_hi, 224
	s_cbranch_scc1 .Lsj_skip6
	v_readlane_b32 vcc_lo, v255, 0
	s_cmp_eq_u32 vcc_lo, 0
	s_cbranch_scc1 .Lsj_skip6
	v_writelane_b32 v201, s0, 0
	v_writelane_b32 v201, s1, 1
	v_writelane_b32 v201, s2, 2
	v_writelane_b32 v201, s3, 3
	v_writelane_b32 v201, s4, 4
	v_writelane_b32 v201, s5, 5
	v_writelane_b32 v201, s6, 6
	v_writelane_b32 v201, s7, 7
	v_writelane_b32 v201, s8, 8
	v_writelane_b32 v201, s9, 9
	v_writelane_b32 v201, s10, 10
	v_writelane_b32 v201, s11, 11
	v_writelane_b32 v201, s12, 12
	v_writelane_b32 v201, s13, 13
	v_writelane_b32 v201, s14, 14
	v_writelane_b32 v201, s15, 15
	v_writelane_b32 v201, s16, 16
	v_writelane_b32 v201, s17, 17
	v_writelane_b32 v201, s18, 18
	v_writelane_b32 v201, s19, 19
	v_writelane_b32 v201, s20, 20
	v_writelane_b32 v201, s21, 21
	v_writelane_b32 v201, s22, 22
	v_writelane_b32 v201, s23, 23
	v_writelane_b32 v201, s24, 24
	v_writelane_b32 v201, s25, 25
	v_writelane_b32 v201, s26, 26
	v_writelane_b32 v201, s27, 27
	v_writelane_b32 v201, s28, 28
	v_writelane_b32 v201, s29, 29
	v_writelane_b32 v201, s30, 30
	v_writelane_b32 v201, s31, 31
	v_writelane_b32 v201, s32, 32
	v_writelane_b32 v201, s33, 33
	v_writelane_b32 v201, s34, 34
	v_writelane_b32 v201, s35, 35
	v_writelane_b32 v201, s36, 36
	v_writelane_b32 v201, s37, 37
	v_writelane_b32 v201, s38, 38
	v_writelane_b32 v201, s39, 39
	v_writelane_b32 v201, s40, 40
	v_writelane_b32 v201, s41, 41
	v_writelane_b32 v201, s42, 42
	v_writelane_b32 v201, s43, 43
	v_writelane_b32 v201, s44, 44
	v_writelane_b32 v201, s45, 45
	v_writelane_b32 v201, s46, 46
	v_writelane_b32 v201, s47, 47
	v_writelane_b32 v201, s48, 48
	v_writelane_b32 v201, s49, 49
	v_writelane_b32 v201, s50, 50
	v_writelane_b32 v201, s51, 51
	v_writelane_b32 v201, s52, 52
	v_writelane_b32 v201, s53, 53
	v_writelane_b32 v201, s54, 54
	v_writelane_b32 v201, s55, 55
	v_writelane_b32 v201, s56, 56
	v_writelane_b32 v201, s57, 57
	v_writelane_b32 v201, s58, 58
	v_writelane_b32 v201, s59, 59
	v_writelane_b32 v201, s60, 60
	v_writelane_b32 v201, s61, 61
	v_writelane_b32 v201, s62, 62
	v_writelane_b32 v201, s63, 63
	v_writelane_b32 v202, s64, 0
	v_writelane_b32 v202, s65, 1
	v_writelane_b32 v202, s66, 2
	v_writelane_b32 v202, s67, 3
	v_writelane_b32 v202, s68, 4
	v_writelane_b32 v202, s69, 5
	v_writelane_b32 v202, s70, 6
	v_writelane_b32 v202, s71, 7
	v_writelane_b32 v202, s72, 8
	v_writelane_b32 v202, s73, 9
	v_writelane_b32 v202, s74, 10
	v_writelane_b32 v202, s75, 11
	v_writelane_b32 v202, s76, 12
	v_writelane_b32 v202, s77, 13
	v_writelane_b32 v202, s78, 14
	v_writelane_b32 v202, s79, 15
	v_writelane_b32 v202, s80, 16
	v_writelane_b32 v202, s81, 17
	v_writelane_b32 v202, s82, 18
	v_writelane_b32 v202, s83, 19
	v_writelane_b32 v202, s84, 20
	v_writelane_b32 v202, s85, 21
	v_writelane_b32 v202, s86, 22
	v_writelane_b32 v202, s87, 23
	v_writelane_b32 v202, s88, 24
	v_writelane_b32 v202, s89, 25
	v_writelane_b32 v202, s90, 26
	v_writelane_b32 v202, s91, 27
	v_writelane_b32 v202, s92, 28
	v_writelane_b32 v202, s93, 29
	v_writelane_b32 v202, s94, 30
	v_writelane_b32 v202, s95, 31
	v_writelane_b32 v202, s96, 32
	v_writelane_b32 v202, s97, 33
	v_writelane_b32 v202, s98, 34
	v_writelane_b32 v202, s99, 35
	v_mov_b32_e32 v200, v1
	v_readlane_b32 vcc_lo, v255, 0
	s_cmp_eq_u32 vcc_lo, 0
	s_cbranch_scc1 .Lsjd_no6_0
	v_readlane_b32 s2, v201, 0
	v_readlane_b32 s3, v201, 1
	v_readlane_b32 s4, v201, 33
	v_readlane_b32 s5, v255, 5
	s_nop 7
	s_load_dwordx2 s[6:7], s[2:3], 0x10
	s_load_dwordx2 s[8:9], s[2:3], 0xb0
	s_sub_i32 s5, s5, 88
	s_and_b32 s5, s5, 0xff
	s_lshl_b32 s5, s5, 9
	v_mbcnt_lo_u32_b32 v0, -1, 0
	v_mbcnt_hi_u32_b32 v0, -1, v0
	v_lshl_or_b32 v0, s4, 6, v0
	v_add_u32_e32 v0, s5, v0
	v_add_u32_e32 v0, 0x5c0000, v0
	s_mov_b32 s10, 0x780000
	s_waitcnt lgkmcnt(0)
	s_add_u32 s8, s8, 0x3bb0800
	s_addc_u32 s9, s9, 0
; DEVI u32x4 pack8(const f32x4 a, const f32x4 b) { u32x4 w; w.x = cvtpk(a[0], a[1]); w.y = cvtpk(a[2], a[3]); w.z = cvtpk(b[0], b[1]); w.w = cvtpk(b[2], b[3]); return w; }
; DEVI const float* IN(int i) { return *(const float* const __attribute__((address_space(4)))*)(kargs() + 8 * i); }
; DEVI void prologue(int wv, LAS unsigned char* lds) {
;     ...
;         const float* cache_ckv = IN(2); bf16_t* ckvb = (bf16_t*)(ws + O_CKVB);
;         for (size_t i = gt; i < (size_t)2 * MC * 256 / 8; i += 8 * NGT) {
;             f32x4 a[8], b[8];
; #pragma unroll
;             for (int k = 0; k < 8; ++k) { const size_t ii = i + k * NGT; if (ii < (size_t)2 * MC * 256 / 8) { a[k] = *(const f32x4*)(cache_ckv + ii * 8); b[k] = *(const f32x4*)(cache_ckv + ii * 8 + 4); } }
; #pragma unroll
;             for (int k = 0; k < 8; ++k) { const size_t ii = i + k * NGT; if (ii < (size_t)2 * MC * 256 / 8) *(u32x4*)(ckvb + ii * 8) = pack8(a[k], b[k]); }
;         }
.Lsjd_loop6_0:
	v_mov_b32_e32 v1, v0
	v_cmp_gt_u32_e64 s[12:13], s10, v1
	v_add_u32_e32 v2, 0x1c000, v0
	v_cmp_gt_u32_e64 s[14:15], s10, v2
	v_add_u32_e32 v3, 0x38000, v0
	v_cmp_gt_u32_e64 s[16:17], s10, v3
	v_add_u32_e32 v4, 0x54000, v0
	v_cmp_gt_u32_e64 s[18:19], s10, v4
	v_add_u32_e32 v5, 0x70000, v0
	v_cmp_gt_u32_e64 s[20:21], s10, v5
	v_add_u32_e32 v6, 0x8c000, v0
	v_cmp_gt_u32_e64 s[22:23], s10, v6
	v_add_u32_e32 v7, 0xa8000, v0
	v_cmp_gt_u32_e64 s[24:25], s10, v7
	v_add_u32_e32 v8, 0xc4000, v0
	v_cmp_gt_u32_e64 s[26:27], s10, v8
	s_mov_b64 exec, s[12:13]
	v_and_b32_e32 v20, 0x3ff, v1
	v_and_b32_e32 v21, 0xfffffc00, v1
	v_lshlrev_b32_e32 v21, 5, v21
	v_and_b32_e32 v22, 31, v20
	v_lshl_or_b32 v21, v22, 10, v21
	v_lshrrev_b32_e32 v22, 8, v20
	v_lshl_or_b32 v21, v22, 8, v21
	v_bfe_u32 v22, v20, 5, 1
	v_lshl_or_b32 v21, v22, 7, v21
	v_bfe_u32 v22, v20, 6, 2
	v_lshl_or_b32 v9, v22, 5, v21
	global_load_dwordx4 v[24:27], v9, s[6:7]
	global_load_dwordx4 v[28:31], v9, s[6:7] offset:16
	s_mov_b64 exec, s[14:15]
	v_and_b32_e32 v20, 0x3ff, v2
	v_and_b32_e32 v21, 0xfffffc00, v2
	v_lshlrev_b32_e32 v21, 5, v21
	v_and_b32_e32 v22, 31, v20
	v_lshl_or_b32 v21, v22, 10, v21
	v_lshrrev_b32_e32 v22, 8, v20
	v_lshl_or_b32 v21, v22, 8, v21
	v_bfe_u32 v22, v20, 5, 1
	v_lshl_or_b32 v21, v22, 7, v21
	v_bfe_u32 v22, v20, 6, 2
	v_lshl_or_b32 v10, v22, 5, v21
	global_load_dwordx4 v[32:35], v10, s[6:7]
	global_load_dwordx4 v[36:39], v10, s[6:7] offset:16
	s_mov_b64 exec, s[16:17]
	v_and_b32_e32 v20, 0x3ff, v3
	v_and_b32_e32 v21, 0xfffffc00, v3
	v_lshlrev_b32_e32 v21, 5, v21
	v_and_b32_e32 v22, 31, v20
	v_lshl_or_b32 v21, v22, 10, v21
	v_lshrrev_b32_e32 v22, 8, v20
	v_lshl_or_b32 v21, v22, 8, v21
	v_bfe_u32 v22, v20, 5, 1
	v_lshl_or_b32 v21, v22, 7, v21
	v_bfe_u32 v22, v20, 6, 2
	v_lshl_or_b32 v11, v22, 5, v21
	global_load_dwordx4 v[40:43], v11, s[6:7]
	global_load_dwordx4 v[44:47], v11, s[6:7] offset:16
	s_mov_b64 exec, s[18:19]
	v_and_b32_e32 v20, 0x3ff, v4
	v_and_b32_e32 v21, 0xfffffc00, v4
	v_lshlrev_b32_e32 v21, 5, v21
	v_and_b32_e32 v22, 31, v20
	v_lshl_or_b32 v21, v22, 10, v21
	v_lshrrev_b32_e32 v22, 8, v20
	v_lshl_or_b32 v21, v22, 8, v21
	v_bfe_u32 v22, v20, 5, 1
	v_lshl_or_b32 v21, v22, 7, v21
	v_bfe_u32 v22, v20, 6, 2
	v_lshl_or_b32 v12, v22, 5, v21
	global_load_dwordx4 v[48:51], v12, s[6:7]
	global_load_dwordx4 v[52:55], v12, s[6:7] offset:16
	s_mov_b64 exec, s[20:21]
	v_and_b32_e32 v20, 0x3ff, v5
	v_and_b32_e32 v21, 0xfffffc00, v5
	v_lshlrev_b32_e32 v21, 5, v21
	v_and_b32_e32 v22, 31, v20
	v_lshl_or_b32 v21, v22, 10, v21
	v_lshrrev_b32_e32 v22, 8, v20
	v_lshl_or_b32 v21, v22, 8, v21
	v_bfe_u32 v22, v20, 5, 1
	v_lshl_or_b32 v21, v22, 7, v21
	v_bfe_u32 v22, v20, 6, 2
	v_lshl_or_b32 v13, v22, 5, v21
	global_load_dwordx4 v[56:59], v13, s[6:7]
	global_load_dwordx4 v[60:63], v13, s[6:7] offset:16
	s_mov_b64 exec, s[22:23]
	v_and_b32_e32 v20, 0x3ff, v6
	v_and_b32_e32 v21, 0xfffffc00, v6
	v_lshlrev_b32_e32 v21, 5, v21
	v_and_b32_e32 v22, 31, v20
	v_lshl_or_b32 v21, v22, 10, v21
	v_lshrrev_b32_e32 v22, 8, v20
	v_lshl_or_b32 v21, v22, 8, v21
	v_bfe_u32 v22, v20, 5, 1
	v_lshl_or_b32 v21, v22, 7, v21
	v_bfe_u32 v22, v20, 6, 2
	v_lshl_or_b32 v14, v22, 5, v21
	global_load_dwordx4 v[64:67], v14, s[6:7]
	global_load_dwordx4 v[68:71], v14, s[6:7] offset:16
	s_mov_b64 exec, s[24:25]
	v_and_b32_e32 v20, 0x3ff, v7
	v_and_b32_e32 v21, 0xfffffc00, v7
	v_lshlrev_b32_e32 v21, 5, v21
	v_and_b32_e32 v22, 31, v20
	v_lshl_or_b32 v21, v22, 10, v21
	v_lshrrev_b32_e32 v22, 8, v20
	v_lshl_or_b32 v21, v22, 8, v21
	v_bfe_u32 v22, v20, 5, 1
	v_lshl_or_b32 v21, v22, 7, v21
	v_bfe_u32 v22, v20, 6, 2
	v_lshl_or_b32 v15, v22, 5, v21
	global_load_dwordx4 v[72:75], v15, s[6:7]
	global_load_dwordx4 v[76:79], v15, s[6:7] offset:16
	s_mov_b64 exec, s[26:27]
	v_and_b32_e32 v20, 0x3ff, v8
	v_and_b32_e32 v21, 0xfffffc00, v8
	v_lshlrev_b32_e32 v21, 5, v21
	v_and_b32_e32 v22, 31, v20
	v_lshl_or_b32 v21, v22, 10, v21
	v_lshrrev_b32_e32 v22, 8, v20
	v_lshl_or_b32 v21, v22, 8, v21
	v_bfe_u32 v22, v20, 5, 1
	v_lshl_or_b32 v21, v22, 7, v21
	v_bfe_u32 v22, v20, 6, 2
	v_lshl_or_b32 v16, v22, 5, v21
	global_load_dwordx4 v[80:83], v16, s[6:7]
	global_load_dwordx4 v[84:87], v16, s[6:7] offset:16
	s_mov_b64 exec, s[12:13]
	s_waitcnt vmcnt(14)
	v_cvt_pk_bf16_f32 v100, v24, v25
	v_cvt_pk_bf16_f32 v101, v26, v27
	v_cvt_pk_bf16_f32 v102, v28, v29
	v_cvt_pk_bf16_f32 v103, v30, v31
	v_lshlrev_b32_e32 v104, 4, v1
	global_store_dwordx4 v104, v[100:103], s[8:9]
	s_mov_b64 exec, s[14:15]
	s_waitcnt vmcnt(12)
	v_cvt_pk_bf16_f32 v106, v32, v33
	v_cvt_pk_bf16_f32 v107, v34, v35
	v_cvt_pk_bf16_f32 v108, v36, v37
	v_cvt_pk_bf16_f32 v109, v38, v39
	v_lshlrev_b32_e32 v110, 4, v2
	global_store_dwordx4 v110, v[106:109], s[8:9]
	s_mov_b64 exec, s[16:17]
	s_waitcnt vmcnt(10)
	v_cvt_pk_bf16_f32 v100, v40, v41
	v_cvt_pk_bf16_f32 v101, v42, v43
	v_cvt_pk_bf16_f32 v102, v44, v45
	v_cvt_pk_bf16_f32 v103, v46, v47
	v_lshlrev_b32_e32 v104, 4, v3
	global_store_dwordx4 v104, v[100:103], s[8:9]
	s_mov_b64 exec, s[18:19]
	s_waitcnt vmcnt(8)
	v_cvt_pk_bf16_f32 v106, v48, v49
	v_cvt_pk_bf16_f32 v107, v50, v51
	v_cvt_pk_bf16_f32 v108, v52, v53
	v_cvt_pk_bf16_f32 v109, v54, v55
	v_lshlrev_b32_e32 v110, 4, v4
	global_store_dwordx4 v110, v[106:109], s[8:9]
	s_mov_b64 exec, s[20:21]
	s_waitcnt vmcnt(6)
	v_cvt_pk_bf16_f32 v100, v56, v57
	v_cvt_pk_bf16_f32 v101, v58, v59
	v_cvt_pk_bf16_f32 v102, v60, v61
	v_cvt_pk_bf16_f32 v103, v62, v63
	v_lshlrev_b32_e32 v104, 4, v5
	global_store_dwordx4 v104, v[100:103], s[8:9]
	s_mov_b64 exec, s[22:23]
	s_waitcnt vmcnt(4)
	v_cvt_pk_bf16_f32 v106, v64, v65
	v_cvt_pk_bf16_f32 v107, v66, v67
	v_cvt_pk_bf16_f32 v108, v68, v69
	v_cvt_pk_bf16_f32 v109, v70, v71
	v_lshlrev_b32_e32 v110, 4, v6
	global_store_dwordx4 v110, v[106:109], s[8:9]
	s_mov_b64 exec, s[24:25]
	s_waitcnt vmcnt(2)
	v_cvt_pk_bf16_f32 v100, v72, v73
	v_cvt_pk_bf16_f32 v101, v74, v75
	v_cvt_pk_bf16_f32 v102, v76, v77
	v_cvt_pk_bf16_f32 v103, v78, v79
	v_lshlrev_b32_e32 v104, 4, v7
	global_store_dwordx4 v104, v[100:103], s[8:9]
	s_mov_b64 exec, s[26:27]
	s_waitcnt vmcnt(0)
	v_cvt_pk_bf16_f32 v106, v80, v81
	v_cvt_pk_bf16_f32 v107, v82, v83
	v_cvt_pk_bf16_f32 v108, v84, v85
	v_cvt_pk_bf16_f32 v109, v86, v87
	v_lshlrev_b32_e32 v110, 4, v8
	global_store_dwordx4 v110, v[106:109], s[8:9]
	s_mov_b64 exec, -1
	v_add_u32_e32 v0, 0xe0000, v0
	v_cmp_gt_u32_e32 vcc, s10, v0
	s_and_b64 vcc, exec, vcc
	s_cbranch_scc1 .Lsjd_loop6_0
